# S5 MFMA waves: next sub-chunk's u fragments read before the barrier (one iteration ahead) so the loop top no longer waits on LDS latency
# speedup vs baseline: 1.0001x; 1.0001x over previous
; #define LAS __attribute__((address_space(3)))
; __device__ __forceinline__ void s5_phase(const Ctx& C, const bf16_t* U, bf16_t* Gout, const float* ABAR, const bf16_t* BB, const bf16_t* CM, const float* Dsk) {
;     ...
;             LDS_BARRIER();
;             for (int i = -1; i <= S5_NS; ++i) {
;                 const bf16x8 uf = g4 < 2 ? *(const LAS bf16x8*)(uring + ((i + 1) & 7) * 512 + uoff) : zero8;
;                 const bf16x8 us = g4 < 2 ? *(const LAS bf16x8*)(uring + ((i - 1) & 7) * 512 + uoff) : zero8;
;                 const LAS unsigned char* src = hb + ((i - 1) & 1) * (S5_SUB * S5_HP) + fr * S5_HP + 16 * g4;
;                 bf16x8 hf[4];
; #pragma unroll
;                 for (int kk = 0; kk < 4; ++kk) hf[kk] = *(const LAS bf16x8*)(src + 64 * kk);
;                 LAS unsigned char* dst = bub + ((i + 1) & 1) * 4096;
;                 f32x4 a[8];
; #pragma unroll
;                 for (int n = 0; n < 8; ++n) a[n] = __builtin_amdgcn_mfma_f32_16x16x32_bf16(uf, bfr[n], (f32x4){0.f, 0.f, 0.f, 0.f}, 0, 0, 0);
;                 f32x4 y1 = __builtin_amdgcn_mfma_f32_16x16x32_bf16(dfr, us, (f32x4){0.f, 0.f, 0.f, 0.f}, 0, 0, 0);
;                 f32x4 y2 = __builtin_amdgcn_mfma_f32_16x16x32_bf16(cfr[2], hf[2], (f32x4){0.f, 0.f, 0.f, 0.f}, 0, 0, 0);
;                 y1 = __builtin_amdgcn_mfma_f32_16x16x32_bf16(cfr[0], hf[0], y1, 0, 0, 0);
;                 y2 = __builtin_amdgcn_mfma_f32_16x16x32_bf16(cfr[3], hf[3], y2, 0, 0, 0);
;                 y1 = __builtin_amdgcn_mfma_f32_16x16x32_bf16(cfr[1], hf[1], y1, 0, 0, 0);
; #pragma unroll
;                 for (int n = 0; n < 4; ++n) { u32x4 w;
;                     w.x = cvt_pk_bf16_c(a[n][0], a[n + 4][0]); w.y = cvt_pk_bf16_c(a[n][1], a[n + 4][1]); w.z = cvt_pk_bf16_c(a[n][2], a[n + 4][2]); w.w = cvt_pk_bf16_c(a[n][3], a[n + 4][3]);
;                     *(LAS u32x4*)(dst + ((g4 * 64) + 16 * n + fr) * 16) = w; }
;                 const f32x4 y = y1 + y2;
;                 if (i >= 1) {
;                     u32x2 o; o.x = cvt_pk_bf16_c(gelu_f(y[0]), gelu_f(y[1])); o.y = cvt_pk_bf16_c(gelu_f(y[2]), gelu_f(y[3]));
;                     *(u32x2*)(Gout + (tokb + 16 * (i - 1) + fr) * DM + 16 * g + 4 * g4) = o;
;                 }
;                 LDS_BARRIER();
;             }
.LBB0_203:
	s_or_b64 exec, exec, s[22:23]
	v_or_b32_e32 v64, v32, v63
	v_lshl_add_u64 v[44:45], v[64:65], 1, v[68:69]
	global_load_dwordx4 v[32:35], v[44:45], off
	global_load_dwordx4 v[36:39], v[44:45], off offset:64
	global_load_dwordx4 v[40:43], v[44:45], off offset:128
	s_nop 0
	global_load_dwordx4 v[44:47], v[44:45], off offset:192
	v_lshlrev_b32_e32 v48, 2, v60
	v_lshl_or_b32 v64, s38, 6, v48
	v_lshl_add_u64 v[48:49], s[60:61], 0, v[64:65]
	v_readlane_b32 s22, v255, 6
	flat_load_dword v48, v[48:49]
	s_waitcnt vmcnt(0) lgkmcnt(0)
	v_cvt_pk_bf16_f32 v51, v48, v65
	v_readlane_b32 s23, v255, 7
	v_and_b32_e32 v52, 0xffff, v51
	v_readlane_b32 s40, v255, 0
	v_cndmask_b32_e64 v48, 0, v52, s[22:23]
	s_mov_b32 s22, 0x5040100
	v_perm_b32 v49, v51, v48, s22
	v_readlane_b32 s41, v255, 1
	s_waitcnt lgkmcnt(0)
	s_barrier
	s_lshl_b32 s96, s38, 5
	v_cndmask_b32_e64 v48, v48, v49, s[40:41]
	v_readlane_b32 s40, v255, 2
	v_readlane_b32 s41, v255, 3
	v_mov_b32_e32 v77, s73
	v_or_b32_e32 v76, s72, v60
	v_cndmask_b32_e64 v49, 0, v52, s[40:41]
	v_readlane_b32 s40, v255, 20
	v_perm_b32 v50, v51, v49, s22
	v_readlane_b32 s41, v255, 21
	v_lshl_add_u64 v[78:79], v[70:71], 0, s[96:97]
	s_movk_i32 s38, 0xc00
	v_cndmask_b32_e64 v49, v49, v50, s[40:41]
	v_readlane_b32 s40, v255, 22
	v_readlane_b32 s41, v255, 23
	s_mov_b32 s72, -2
	s_movk_i32 s96, 0xffe0
	v_cndmask_b32_e64 v50, 0, v52, s[40:41]
	v_cndmask_b32_e64 v52, 0, v52, s[56:57]
	v_perm_b32 v53, v51, v50, s22
	v_perm_b32 v51, v51, v52, s22
	v_cndmask_b32_e64 v50, v50, v53, s[54:55]
	v_cndmask_b32_e64 v51, v52, v51, s[58:59]
	v_mov_b32_e32 v52, 0
	v_mov_b32_e32 v56, 0
	v_mov_b32_e32 v57, 0
	v_mov_b32_e32 v58, 0
	v_mov_b32_e32 v59, 0
	s_and_saveexec_b64 s[80:81], s[42:43]
	s_add_i32 s40, s38, 0xfffff400
	s_and_b32 s40, s40, 0xe00
	v_add_u32_e32 v53, s40, v83
	ds_read_b128 v[56:59], v53
	s_or_b64 exec, exec, s[80:81]
	v_mov_b32_e32 v53, 0
	v_mov_b32_e32 v54, 0
	v_mov_b32_e32 v55, 0
	s_and_saveexec_b64 s[80:81], s[42:43]
	s_and_b32 s40, s38, 0xe00
	v_add_u32_e32 v52, s40, v83
	ds_read_b128 v[52:55], v52
	s_or_b64 exec, exec, s[80:81]
	s_branch .LBB0_205
.Lmy_s5_early:
	s_nop 7
	s_nop 7
.LBB0_204:
	v_mov_b32_e32 v52, 0
	v_mov_b32_e32 v56, 0
	v_mov_b32_e32 v57, 0
	v_mov_b32_e32 v58, 0
	v_mov_b32_e32 v59, 0
	s_and_saveexec_b64 s[80:81], s[42:43]
	s_add_i32 s40, s38, 0xfffff600
	s_and_b32 s40, s40, 0xe00
	v_add_u32_e32 v53, s40, v83
	ds_read_b128 v[56:59], v53
	s_or_b64 exec, exec, s[80:81]
	v_mov_b32_e32 v53, 0
	v_mov_b32_e32 v54, 0
	v_mov_b32_e32 v55, 0
	s_and_saveexec_b64 s[80:81], s[42:43]
	s_add_i32 s40, s38, 0x200
	s_and_b32 s40, s40, 0xe00
	v_add_u32_e32 v52, s40, v83
	ds_read_b128 v[52:55], v52
	s_or_b64 exec, exec, s[80:81]
	s_waitcnt lgkmcnt(2)
	s_barrier
	s_addk_i32 s38, 0x200
	s_addk_i32 s39, 0x1000
	s_add_i32 s96, s96, 16
	s_cmpk_eq_i32 s22, 0x100
	s_mov_b32 s72, s22
	s_cbranch_scc1 .LBB0_173
.LBB0_205:
	s_add_i32 s22, s72, 1
	s_waitcnt lgkmcnt(0)
	v_mfma_f32_16x16x32_bf16 v[86:89], v[56:59], v[4:7], 0
	s_bitcmp1_b32 s72, 0
	s_cselect_b32 s23, 0x1100, 0
	v_add_u32_e32 v64, s23, v84
	v_mfma_f32_16x16x32_bf16 v[110:113], v[56:59], v[16:19], 0
	ds_read_b128 v[102:105], v64
	ds_read_b128 v[106:109], v64 offset:64
	ds_read_b128 v[114:117], v64 offset:128
	ds_read_b128 v[118:121], v64 offset:192
	s_and_b32 s23, s39, 0x1000
	v_mfma_f32_16x16x32_bf16 v[90:93], v[56:59], v[0:3], 0
	s_nop 1
	v_cvt_pk_bf16_f32 v86, v86, v110
	v_cvt_pk_bf16_f32 v87, v87, v111
	v_cvt_pk_bf16_f32 v88, v88, v112
	v_mfma_f32_16x16x32_bf16 v[122:125], v[56:59], v[24:27], 0
	v_cvt_pk_bf16_f32 v89, v89, v113
	v_add_u32_e32 v64, s23, v85
	ds_write_b128 v64, v[86:89]
	v_mfma_f32_16x16x32_bf16 v[94:97], v[56:59], v[12:15], 0
	s_cmp_lt_i32 s22, 1
	s_nop 2
	v_cvt_pk_bf16_f32 v86, v90, v122
	v_cvt_pk_bf16_f32 v87, v91, v123
	v_mfma_f32_16x16x32_bf16 v[126:129], v[56:59], v[20:23], 0
	v_cvt_pk_bf16_f32 v88, v92, v124
	v_cvt_pk_bf16_f32 v89, v93, v125
	ds_write_b128 v64, v[86:89] offset:256
	v_mfma_f32_16x16x32_bf16 v[52:55], v[48:51], v[52:55], 0
	v_mfma_f32_16x16x32_bf16 v[98:101], v[56:59], v[8:11], 0
	s_nop 2
	v_cvt_pk_bf16_f32 v86, v94, v126
	v_cvt_pk_bf16_f32 v87, v95, v127
	v_cvt_pk_bf16_f32 v88, v96, v128
	v_mfma_f32_16x16x32_bf16 v[56:59], v[56:59], v[28:31], 0
	v_cvt_pk_bf16_f32 v89, v97, v129
	ds_write_b128 v64, v[86:89] offset:512
	s_waitcnt lgkmcnt(4)
	v_mfma_f32_16x16x32_bf16 v[90:93], v[40:43], v[114:117], 0
	v_mfma_f32_16x16x32_bf16 v[86:89], v[32:35], v[102:105], v[52:55]
	s_nop 2
	v_cvt_pk_bf16_f32 v56, v98, v56
	v_cvt_pk_bf16_f32 v57, v99, v57
	v_cvt_pk_bf16_f32 v58, v100, v58
	v_cvt_pk_bf16_f32 v59, v101, v59
	s_waitcnt lgkmcnt(3)
	v_mfma_f32_16x16x32_bf16 v[52:55], v[44:47], v[118:121], v[90:93]
	ds_write_b128 v64, v[56:59] offset:768
	v_mfma_f32_16x16x32_bf16 v[56:59], v[36:39], v[106:109], v[86:89]
	s_cbranch_scc1 .Lmy_s5_early
	s_nop 6
	v_pk_add_f32 v[52:53], v[52:53], v[56:57]
	v_pk_add_f32 v[54:55], v[54:55], v[58:59]
	v_mul_f32_e32 v56, 0x3d372713, v52
	v_mul_f32_e32 v57, 0x3d372713, v53
	v_mul_f32_e32 v58, 0x3d372713, v54
	v_mul_f32_e32 v59, 0x3d372713, v55
	v_fma_f32 v56, v52, v56, 1.0
	v_fma_f32 v57, v53, v57, 1.0
	v_fma_f32 v58, v54, v58, 1.0
	v_fma_f32 v59, v55, v59, 1.0
	v_mul_f32_e32 v56, v52, v56
	v_mul_f32_e32 v57, v53, v57
	v_mul_f32_e32 v58, v54, v58
	v_mul_f32_e32 v59, v55, v59
	v_mul_f32_e32 v56, 0xc0135761, v56
	v_mul_f32_e32 v57, 0xc0135761, v57
	v_mul_f32_e32 v58, 0xc0135761, v58
	v_mul_f32_e32 v59, 0xc0135761, v59
	v_exp_f32_e32 v56, v56
	v_exp_f32_e32 v57, v57
	v_exp_f32_e32 v58, v58
	v_exp_f32_e32 v59, v59
	v_add_f32_e32 v56, 1.0, v56
	v_add_f32_e32 v57, 1.0, v57
	v_add_f32_e32 v58, 1.0, v58
	v_add_f32_e32 v59, 1.0, v59
	v_rcp_f32_e32 v56, v56
	v_rcp_f32_e32 v57, v57
	v_rcp_f32_e32 v58, v58
	v_rcp_f32_e32 v59, v59
	v_pk_mul_f32 v[52:53], v[52:53], v[56:57]
	s_nop 0
	v_cvt_pk_bf16_f32 v52, v52, v53
	v_pk_mul_f32 v[54:55], v[54:55], v[58:59]
	s_nop 0
	v_cvt_pk_bf16_f32 v53, v54, v55
	v_lshl_add_u64 v[54:55], v[76:77], 0, s[96:97]
	v_lshlrev_b64 v[54:55], 12, v[54:55]
	v_lshl_add_u64 v[54:55], v[78:79], 0, v[54:55]
	global_store_dwordx2 v[54:55], v[52:53], off
	s_branch .LBB0_204
